# MLA loops: waves 4-7 defer each tile's PV MFMAs to their next iteration (stagger), K/V staging as 3-slot LDS ring
# baseline (speedup 1.0000x reference)
; #define LAS __attribute__((address_space(3)))
; DI int opaque_tid() { int t = threadIdx.x; asm volatile("" : "+v"(t)); return t; }
;     DI const bf16_t* Q() const { return (const bf16_t*)(ws + WS_Q); }
;     DI const bf16_t* KV() const { return (const bf16_t*)(ws + WS_KV); }
;     DI const bf16_t* KPE() const { return (const bf16_t*)(ws + WS_KPE); }
; #define MLA_LOAD() do { sreg[0] = *(const u32x4*)(kp0); sreg[1] = *(const u32x4*)(kp0 + 64); sreg[2] = *(const u32x4*)(kp0 + 128); sreg[3] = *(const u32x4*)(kp0 + 192); \
;         sreg[4] = *(const u32x4*)(kp1); kp0 += (size_t)64 * 2048; kp1 += (size_t)64 * 64; } while (0)
; #define MLA_WRITE(buf) do { LAS unsigned char* kd_ = lds + (buf) * BUFB + lkey * KSTR + lq * 16; LAS unsigned char* vd_ = lds + (buf) * BUFB + 64 * KSTR + lkey * VSTR + lq * 16; \
;         *(LAS u32x4*)(kd_) = sreg[0]; *(LAS u32x4*)(kd_ + 128) = sreg[1]; *(LAS u32x4*)(kd_ + 256) = sreg[4]; *(LAS u32x4*)(vd_) = sreg[2]; *(LAS u32x4*)(vd_ + 128) = sreg[3]; } while (0)
; template <bool ATOM>
; DI void mla_unit(LAS unsigned char* lds, const AttnPtrs& P, int b, int hd, int qb) {
;     constexpr int KSTR = 400, VSTR = 288, NKK = 12, NDV = 4, BUFB = 64 * KSTR + 64 * VSTR;
;     const int tid = opaque_tid(), lane = tid & 63, wid = __builtin_amdgcn_readfirstlane(tid >> 6), r = lane & 31, h = lane >> 5, rg = wid & 3, kh = wid >> 2;
;     const int fq_ = qb * 128 + rg * 32 + r;
;     const size_t tokq = (size_t)b * 2048 + fq_;
;     bf16x8 qf[NKK];
;     { const bf16_t* qp = P.Q() + tokq * 1536 + hd * 192;
; #pragma unroll
;       for (int kk = 0; kk < NKK; ++kk) qf[kk] = *(const bf16x8*)(qp + kk * 16 + 8 * h); }
;     f32x16 o[NDV];
; #pragma unroll
;     for (int d = 0; d < NDV; ++d)
; #pragma unroll
;         for (int i = 0; i < 16; ++i) o[d][i] = 0.f;
;     float mrun = -INFINITY, lrun = 0.f;
;     const int lkey = tid >> 3, lq = tid & 7;
;     const bf16_t* kp0 = P.KV() + ((size_t)b * 2048 + lkey) * 2048 + hd * 256 + lq * 8;
;     const bf16_t* kp1 = P.KPE() + ((size_t)b * 2048 + lkey) * 64 + lq * 8;
;     u32x4 sreg[5];
;     ...
;     const int nsteps = 2 * (qb + 1);
;     __syncthreads();
;     MLA_LOAD(); MLA_WRITE(0);
;     MLA_LOAD();
;     __syncthreads();
;     const int kwo = (kh * 32 + r) * KSTR + h * 16;
;     const int vwo = 64 * KSTR + (kh * 32 + 4 * h + ((lane & 15) >> 2)) * VSTR + (16 * ((lane >> 4) & 1) + 4 * (lane & 3)) * 2;
.LBB0_1048:
	s_and_b64 s[14:15], s[8:9], exec
	v_mov_b32_e32 v30, v188
	s_cselect_b32 s4, s1, s0
	s_and_b32 s16, s4, 7
	v_readfirstlane_b32 s18, v30
	s_bfe_u32 s19, s18, 0x20006
	s_ashr_i32 s14, s4, 6
	s_lshl_b32 s23, s16, 7
	s_lshl_b32 s15, s19, 5
	v_and_b32_e32 v31, 31, v30
	s_or_b32 s34, s15, s23
	s_ashr_i32 s15, s14, 31
	v_or_b32_e32 v214, s34, v31
	s_lshl_b64 s[50:51], s[14:15], 11
	s_bfe_u32 s4, s4, 0x30003
	v_or_b32_e32 v130, s50, v214
	s_waitcnt lgkmcnt(0)
	v_mov_b64_e32 v[0:1], s[10:11]
	v_mad_u64_u32 v[0:1], s[14:15], v130, s90, v[0:1]
	s_mul_i32 s17, s4, 0xc0
	v_bfe_u32 v32, v30, 5, 1
	v_mad_i32_i24 v1, s51, v207, v1
	s_lshl_b32 s38, s17, 1
	v_lshl_add_u64 v[0:1], v[0:1], 0, s[38:39]
	v_lshlrev_b32_e32 v128, 4, v32
	v_ashrrev_i32_e32 v20, 3, v30
	v_lshl_add_u64 v[0:1], v[0:1], 0, v[128:129]
	v_ashrrev_i32_e32 v21, 31, v20
	global_load_dwordx4 v[180:183], v[0:1], off
	global_load_dwordx4 v[176:179], v[0:1], off offset:32
	global_load_dwordx4 v[172:175], v[0:1], off offset:64
	global_load_dwordx4 v[168:171], v[0:1], off offset:96
	global_load_dwordx4 v[164:167], v[0:1], off offset:128
	global_load_dwordx4 v[160:163], v[0:1], off offset:160
	global_load_dwordx4 v[156:159], v[0:1], off offset:192
	global_load_dwordx4 v[152:155], v[0:1], off offset:224
	global_load_dwordx4 v[148:151], v[0:1], off offset:256
	global_load_dwordx4 v[144:147], v[0:1], off offset:288
	global_load_dwordx4 v[140:143], v[0:1], off offset:320
	global_load_dwordx4 v[136:139], v[0:1], off offset:352
	v_lshl_add_u64 v[0:1], s[50:51], 0, v[20:21]
	v_lshlrev_b64 v[2:3], 12, v[0:1]
	v_lshlrev_b32_e32 v4, 4, v30
	v_lshlrev_b64 v[0:1], 7, v[0:1]
	v_lshl_add_u64 v[2:3], s[12:13], 0, v[2:3]
	s_lshl_b32 s38, s4, 9
	v_and_b32_e32 v116, 0x70, v4
	v_mov_b32_e32 v117, v129
	v_lshl_add_u64 v[0:1], s[42:43], 0, v[0:1]
	v_lshl_add_u64 v[2:3], v[2:3], 0, s[38:39]
	v_lshl_add_u64 v[24:25], v[0:1], 0, v[116:117]
	v_lshl_add_u64 v[22:23], v[2:3], 0, v[116:117]
	s_barrier
	global_load_dwordx4 v[0:3], v[24:25], off
	global_load_dwordx4 v[4:7], v[22:23], off
	global_load_dwordx4 v[8:11], v[22:23], off offset:128
	global_load_dwordx4 v[12:15], v[22:23], off offset:256
	global_load_dwordx4 v[16:19], v[22:23], off offset:384
	v_add_co_u32_e32 v26, vcc, s89, v22
	s_movk_i32 s14, 0x2000
	s_nop 0
	v_addc_co_u32_e32 v27, vcc, 0, v23, vcc
	global_load_dwordx4 v[96:99], v[26:27], off
	global_load_dwordx4 v[100:103], v[26:27], off offset:128
	global_load_dwordx4 v[104:107], v[26:27], off offset:256
	v_add_co_u32_e32 v28, vcc, s14, v24
	s_lshl_b32 s48, s4, 8
	s_nop 0
	v_addc_co_u32_e32 v29, vcc, 0, v25, vcc
	global_load_dwordx4 v[108:111], v[26:27], off offset:384
	global_load_dwordx4 v[112:115], v[28:29], off
	s_movk_i32 s4, 0x190
	v_mul_lo_u32 v117, v20, s4
	s_ashr_i32 s22, s18, 8
	s_movk_i32 s38, 0x120
	v_add3_u32 v26, 0, v117, v116
	s_movk_i32 s35, 0xff90
	v_mul_lo_u32 v122, v20, s38
	v_mad_u64_u32 v[20:21], s[36:37], v20, s35, v[26:27]
	s_lshl_b32 s35, s22, 5
	v_lshlrev_b32_e32 v209, 2, v32
	s_mov_b64 s[36:37], 0x4000
	v_and_b32_e32 v208, 63, v30
	v_lshl_add_u64 v[118:119], v[24:25], 0, s[36:37]
	s_mov_b64 s[36:37], 0x80000
	v_lshl_add_u64 v[120:121], v[22:23], 0, s[36:37]
	v_mov_b32_e32 v21, v129
	v_mov_b32_e32 v22, v129
	v_mov_b32_e32 v23, v129
	v_mov_b32_e32 v24, v129
	v_mov_b32_e32 v25, v129
	v_mov_b32_e32 v27, v129
	v_mov_b32_e32 v28, v129
	v_mov_b32_e32 v29, v129
	s_mov_b32 s14, 0
	s_lshl_b32 s15, s16, 1
	v_mov_b32_e32 v131, s51
	s_or_b32 s36, s34, 31
	s_or_b32 s37, s23, 64
	v_or_b32_e32 v123, s35, v209
	v_mov_b32_e32 v213, 0
	v_mov_b32_e32 v124, 0xff800000
	s_waitcnt vmcnt(9)
	ds_write_b128 v26, v[0:3] offset:256
	s_waitcnt vmcnt(8)
	ds_write_b128 v26, v[4:7]
	s_waitcnt vmcnt(7)
	ds_write_b128 v26, v[8:11] offset:128
	s_waitcnt vmcnt(6)
	ds_write_b128 v20, v[12:15] offset:25600
	s_waitcnt vmcnt(5)
	ds_write_b128 v20, v[16:19] offset:25728
	v_or_b32_e32 v0, s35, v31
	v_mul_lo_u32 v215, v0, s4
	v_bfe_u32 v0, v30, 2, 2
	v_or3_b32 v0, v209, v0, s35
	v_mul_lo_u32 v210, v0, s38
	v_and_b32_e32 v0, 16, v30
	v_lshlrev_b32_e32 v1, 2, v30
	v_mov_b32_e32 v30, v129
	v_mov_b32_e32 v31, v129
	v_and_or_b32 v0, v1, 12, v0
	v_mov_b32_e32 v16, v129
	v_mov_b32_e32 v17, v129
	v_mov_b32_e32 v18, v129
	v_mov_b32_e32 v19, v129
	v_mov_b32_e32 v20, v129
	v_mov_b32_e32 v26, v129
	v_mov_b64_e32 v[46:47], v[30:31]
	v_mov_b64_e32 v[62:63], v[30:31]
	v_mov_b64_e32 v[78:79], v[30:31]
	v_lshlrev_b32_e32 v211, 1, v0
	v_mov_b64_e32 v[44:45], v[28:29]
	v_mov_b64_e32 v[42:43], v[26:27]
	v_mov_b64_e32 v[40:41], v[24:25]
	v_mov_b64_e32 v[38:39], v[22:23]
	v_mov_b64_e32 v[36:37], v[20:21]
	v_mov_b64_e32 v[34:35], v[18:19]
	v_mov_b64_e32 v[32:33], v[16:17]
	v_mov_b64_e32 v[60:61], v[28:29]
	v_mov_b64_e32 v[58:59], v[26:27]
	v_mov_b64_e32 v[56:57], v[24:25]
	v_mov_b64_e32 v[54:55], v[22:23]
	v_mov_b64_e32 v[52:53], v[20:21]
	v_mov_b64_e32 v[50:51], v[18:19]
	v_mov_b64_e32 v[48:49], v[16:17]
	v_mov_b64_e32 v[76:77], v[28:29]
	v_mov_b64_e32 v[74:75], v[26:27]
	v_mov_b64_e32 v[72:73], v[24:25]
	v_mov_b64_e32 v[70:71], v[22:23]
	v_mov_b64_e32 v[68:69], v[20:21]
	v_mov_b64_e32 v[66:67], v[18:19]
	v_mov_b64_e32 v[64:65], v[16:17]
	s_mov_b32 s4, 0
	s_waitcnt lgkmcnt(0)
	s_barrier
	s_mov_b32 s100, 0
	s_mov_b32 s101, 0
; #define LAS __attribute__((address_space(3)))
; template <bool ATOM>
; DI void mla_unit(LAS unsigned char* lds, const AttnPtrs& P, int b, int hd, int qb) {
;     ...
;     for (int t = 0; t < nsteps; ++t) {
;         if (t + 1 < nsteps) MLA_WRITE((t + 1) & 1);
;         if (t + 2 < nsteps) MLA_LOAD();
;         const int keyb = t * 64 + kh * 32;
;         if (keyb <= qb * 128 + rg * 32 + 31) {
;             const LAS unsigned char* Kw = lds + (t & 1) * BUFB + kwo;
;             const LAS unsigned char* Vw = lds + (t & 1) * BUFB + vwo;
;             f32x16 xa, xb;
; #pragma unroll
;             for (int i = 0; i < 16; ++i) { xa[i] = 0.f; xb[i] = 0.f; }
; #pragma unroll
;             for (int kk = 0; kk < NKK; kk += 2) {
;                 const bf16x8 a0 = *(const LAS bf16x8*)(Kw + kk * 32), a1 = *(const LAS bf16x8*)(Kw + kk * 32 + 32);
;                 xa = MFMA32(a0, qf[kk], xa); xb = MFMA32(a1, qf[kk + 1], xb);
;                 if ((kk & 3) == 2) __builtin_amdgcn_sched_barrier(0);
;             }
;             f32x16 x0;
; #pragma unroll
;             for (int i = 0; i < 16; ++i) x0[i] = xa[i] + xb[i];
;             if (keyb + 31 > qb * 128 + rg * 32) {
; #pragma unroll
;                 for (int i = 0; i < 16; ++i) if (keyb + crow(i, h) > fq_) x0[i] = -INFINITY;
;             }
;             float mloc = x0[0];
; #pragma unroll
;             for (int i = 1; i < 16; ++i) mloc = fmaxf(mloc, x0[i]);
;             mloc = fmaxf(mloc, __shfl_xor(mloc, 32));
;             const float mnew = fmaxf(mrun, mloc);
;             const float msafe = mnew == -INFINITY ? 0.f : mnew;
;             const float alpha = fexp2(mrun - msafe);
;             float psum = 0.f;
; #pragma unroll
;             for (int i = 0; i < 16; ++i) { x0[i] = fexp2(x0[i] - msafe); psum += x0[i]; }
;             lrun = lrun * alpha + psum; mrun = mnew;
;             if (__builtin_amdgcn_ballot_w64(alpha != 1.f) != 0ull) {
; #pragma unroll
;                 for (int d = 0; d < NDV; ++d)
; #pragma unroll
;                     for (int i = 0; i < 16; ++i) o[d][i] *= alpha;
;             }
; #pragma unroll
;             for (int s2 = 0; s2 < 2; ++s2) {
;                 const bf16x8 pf = pack_step(x0, s2);
; #pragma unroll
;                 for (int d = 0; d < NDV; ++d) {
;                     const s16x4 lo = vtr(Vw + (16 * s2) * VSTR + d * 64), hi = vtr(Vw + (16 * s2 + 8) * VSTR + d * 64);
.LBB0_1049:
	s_add_i32 s38, s4, 1
	s_add_i32 s23, s100, 0xac00
	s_cmp_eq_u32 s23, 0x20400
	s_cselect_b32 s23, 0, s23
	v_add3_u32 v190, s23, v117, v116
	v_add3_u32 v192, s23, v122, v116
	s_cmp_ge_u32 s4, s15
	s_waitcnt vmcnt(4)
	ds_write_b128 v190, v[96:99]
	s_waitcnt vmcnt(3)
	ds_write_b128 v190, v[100:103] offset:128
	s_waitcnt vmcnt(0)
	ds_write_b128 v190, v[112:115] offset:256
	ds_write_b128 v192, v[104:107] offset:25600
	ds_write_b128 v192, v[108:111] offset:25728
	s_cbranch_scc1 .LBB0_1051
	global_load_dwordx4 v[96:99], v[120:121], off
	global_load_dwordx4 v[100:103], v[120:121], off offset:128
	global_load_dwordx4 v[104:107], v[120:121], off offset:256
	global_load_dwordx4 v[108:111], v[120:121], off offset:384
	global_load_dwordx4 v[112:115], v[118:119], off
	v_lshl_add_u64 v[120:121], v[120:121], 0, s[20:21]
	v_lshl_add_u64 v[118:119], v[118:119], 0, s[24:25]
.LBB0_1051:
	s_cmp_eq_u32 s101, 0
	s_cbranch_scc1 .Lmla_nopend_1
	s_sub_i32 s40, s100, 0xac00
	s_cmp_lt_i32 s40, 0
	s_cselect_b32 s40, 0x15800, s40
	v_add3_u32 v80, s40, v210, v211
	ds_read_b64_tr_b16 v[216:217], v80 offset:25600
	ds_read_b64_tr_b16 v[218:219], v80 offset:27904
	ds_read_b64_tr_b16 v[220:221], v80 offset:25664
	ds_read_b64_tr_b16 v[222:223], v80 offset:27968
	ds_read_b64_tr_b16 v[224:225], v80 offset:25728
	ds_read_b64_tr_b16 v[226:227], v80 offset:28032
	ds_read_b64_tr_b16 v[228:229], v80 offset:25792
	ds_read_b64_tr_b16 v[230:231], v80 offset:28096
	ds_read_b64_tr_b16 v[232:233], v80 offset:30208
	ds_read_b64_tr_b16 v[234:235], v80 offset:32512
	ds_read_b64_tr_b16 v[236:237], v80 offset:30272
	ds_read_b64_tr_b16 v[238:239], v80 offset:32576
	s_waitcnt lgkmcnt(10)
	v_mfma_f32_32x32x16_bf16 v[64:79], v[216:219], v[0:3], v[64:79]
	ds_read_b64_tr_b16 v[240:241], v80 offset:30336
	ds_read_b64_tr_b16 v[242:243], v80 offset:32640
	s_waitcnt lgkmcnt(10)
	v_mfma_f32_32x32x16_bf16 v[48:63], v[220:223], v[0:3], v[48:63]
	ds_read_b64_tr_b16 v[244:245], v80 offset:30400
	ds_read_b64_tr_b16 v[246:247], v80 offset:32704
	s_waitcnt lgkmcnt(10)
	v_mfma_f32_32x32x16_bf16 v[32:47], v[224:227], v[0:3], v[32:47]
	s_waitcnt lgkmcnt(8)
	v_mfma_f32_32x32x16_bf16 v[16:31], v[228:231], v[0:3], v[16:31]
	s_waitcnt lgkmcnt(6)
	v_mfma_f32_32x32x16_bf16 v[64:79], v[232:235], v[4:7], v[64:79]
	s_waitcnt lgkmcnt(4)
	v_mfma_f32_32x32x16_bf16 v[48:63], v[236:239], v[4:7], v[48:63]
	s_waitcnt lgkmcnt(2)
	v_mfma_f32_32x32x16_bf16 v[32:47], v[240:243], v[4:7], v[32:47]
	s_waitcnt lgkmcnt(0)
	v_mfma_f32_32x32x16_bf16 v[16:31], v[244:247], v[4:7], v[16:31]
	s_nop 7
	s_nop 3
	s_mov_b32 s101, 0
.Lmla_nopend_1:
	s_add_i32 s40, s35, s14
	s_cmp_gt_i32 s40, s36
	s_cbranch_scc1 .LBB0_1057
	s_mov_b32 s4, s100
	v_add3_u32 v125, s4, v215, v128
	ds_read_b128 v[0:3], v125
	ds_read_b128 v[80:83], v125 offset:32
	ds_read_b128 v[216:219], v125 offset:64
	s_waitcnt lgkmcnt(2)
	v_mfma_f32_32x32x16_bf16 v[0:15], v[0:3], v[180:183], 0
	s_waitcnt lgkmcnt(0)
	v_mfma_f32_32x32x16_bf16 v[0:15], v[216:219], v[172:175], v[0:15]
	ds_read_b128 v[216:219], v125 offset:96
	v_mfma_f32_32x32x16_bf16 v[0:15], v[80:83], v[176:179], v[0:15]
	s_waitcnt lgkmcnt(0)
	v_mfma_f32_32x32x16_bf16 v[0:15], v[216:219], v[168:171], v[0:15]
	ds_read_b128 v[216:219], v125 offset:128
	s_waitcnt lgkmcnt(0)
	v_mfma_f32_32x32x16_bf16 v[0:15], v[216:219], v[164:167], v[0:15]
	ds_read_b128 v[216:219], v125 offset:160
	s_waitcnt lgkmcnt(0)
	v_mfma_f32_32x32x16_bf16 v[0:15], v[216:219], v[160:163], v[0:15]
	ds_read_b128 v[216:219], v125 offset:192
	s_waitcnt lgkmcnt(0)
	v_mfma_f32_32x32x16_bf16 v[0:15], v[216:219], v[156:159], v[0:15]
	ds_read_b128 v[216:219], v125 offset:224
	s_waitcnt lgkmcnt(0)
	v_mfma_f32_32x32x16_bf16 v[0:15], v[216:219], v[152:155], v[0:15]
	ds_read_b128 v[216:219], v125 offset:256
	s_waitcnt lgkmcnt(0)
	v_mfma_f32_32x32x16_bf16 v[0:15], v[216:219], v[148:151], v[0:15]
	ds_read_b128 v[216:219], v125 offset:288
	s_waitcnt lgkmcnt(0)
	v_mfma_f32_32x32x16_bf16 v[0:15], v[216:219], v[144:147], v[0:15]
	ds_read_b128 v[216:219], v125 offset:320
	s_waitcnt lgkmcnt(0)
	v_mfma_f32_32x32x16_bf16 v[0:15], v[216:219], v[140:143], v[0:15]
	ds_read_b128 v[216:219], v125 offset:352
	s_waitcnt lgkmcnt(0)
	v_mfma_f32_32x32x16_bf16 v[0:15], v[216:219], v[136:139], v[0:15]
	s_add_i32 s40, s40, 31
	s_nop 10
	v_mov_b32_e32 v80, v0
	v_mov_b32_e32 v81, v1
	s_cmp_le_i32 s40, s34
	s_cbranch_scc1 .LBB0_1054
	v_add_u32_e32 v0, s14, v123
	v_cmp_lt_i32_e32 vcc, v0, v214
	v_add_u32_e32 v1, 2, v0
	s_nop 0
	v_cndmask_b32_e32 v81, v205, v81, vcc
	v_cmp_le_i32_e32 vcc, v0, v214
	s_nop 1
	v_cndmask_b32_e32 v80, v205, v80, vcc
	v_cmp_le_i32_e32 vcc, v1, v214
	v_add_u32_e32 v1, 3, v0
	s_nop 0
	v_cndmask_b32_e32 v2, v205, v2, vcc
	v_cmp_le_i32_e32 vcc, v1, v214
	v_add_u32_e32 v1, 8, v0
	s_nop 0
	v_cndmask_b32_e32 v3, v205, v3, vcc
	v_cmp_le_i32_e32 vcc, v1, v214
	v_add_u32_e32 v1, 9, v0
	s_nop 0
	v_cndmask_b32_e32 v4, v205, v4, vcc
	v_cmp_le_i32_e32 vcc, v1, v214
	v_add_u32_e32 v1, 10, v0
	s_nop 0
	v_cndmask_b32_e32 v5, v205, v5, vcc
	v_cmp_le_i32_e32 vcc, v1, v214
	v_add_u32_e32 v1, 11, v0
	s_nop 0
	v_cndmask_b32_e32 v6, v205, v6, vcc
	v_cmp_le_i32_e32 vcc, v1, v214
	v_add_u32_e32 v1, 16, v0
	s_nop 0
	v_cndmask_b32_e32 v7, v205, v7, vcc
	v_cmp_le_i32_e32 vcc, v1, v214
	v_add_u32_e32 v1, 17, v0
	s_nop 0
	v_cndmask_b32_e32 v8, v205, v8, vcc
	v_cmp_le_i32_e32 vcc, v1, v214
	v_add_u32_e32 v1, 18, v0
	s_nop 0
	v_cndmask_b32_e32 v9, v205, v9, vcc
	v_cmp_le_i32_e32 vcc, v1, v214
	v_add_u32_e32 v1, 19, v0
	s_nop 0
	v_cndmask_b32_e32 v10, v205, v10, vcc
	v_cmp_le_i32_e32 vcc, v1, v214
	v_add_u32_e32 v1, 24, v0
	s_nop 0
	v_cndmask_b32_e32 v11, v205, v11, vcc
	v_cmp_le_i32_e32 vcc, v1, v214
	v_add_u32_e32 v1, 25, v0
	s_nop 0
	v_cndmask_b32_e32 v12, v205, v12, vcc
	v_cmp_le_i32_e32 vcc, v1, v214
	v_add_u32_e32 v1, 26, v0
	v_add_u32_e32 v0, 27, v0
	v_cndmask_b32_e32 v13, v205, v13, vcc
	v_cmp_le_i32_e32 vcc, v1, v214
	s_nop 1
	v_cndmask_b32_e32 v14, v205, v14, vcc
	v_cmp_le_i32_e32 vcc, v0, v214
	s_nop 1
	v_cndmask_b32_e32 v15, v205, v15, vcc

; DI float fexp2(float x) { return __builtin_amdgcn_exp2f(x); }
; DI s16x4 vtr(const LAS unsigned char* p) { return __builtin_bit_cast(s16x4, __builtin_amdgcn_ds_read_tr16_b64_v4i16((LAS v4i16_t*)p)); }
; #define MFMA32(a, b, c) __builtin_amdgcn_mfma_f32_32x32x16_bf16((a), (b), (c), 0, 0, 0)
; template <bool ATOM>
; DI void mla_unit(LAS unsigned char* lds, const AttnPtrs& P, int b, int hd, int qb) {
;     ...
;             for (int i = 0; i < 16; ++i) { x0[i] = fexp2(x0[i] - msafe); psum += x0[i]; }
;             lrun = lrun * alpha + psum; mrun = mnew;
;             if (__builtin_amdgcn_ballot_w64(alpha != 1.f) != 0ull) {
; #pragma unroll
;                 for (int d = 0; d < NDV; ++d)
; #pragma unroll
;                     for (int i = 0; i < 16; ++i) o[d][i] *= alpha;
;             }
; #pragma unroll
;             for (int s2 = 0; s2 < 2; ++s2) {
;                 const bf16x8 pf = pack_step(x0, s2);
; #pragma unroll
;                 for (int d = 0; d < NDV; ++d) {
;                     const s16x4 lo = vtr(Vw + (16 * s2) * VSTR + d * 64), hi = vtr(Vw + (16 * s2 + 8) * VSTR + d * 64);
;                     const bf16x8 pa = __builtin_shufflevector(lo, hi, 0, 1, 2, 3, 4, 5, 6, 7);
;                     o[d] = MFMA32(pa, pf, o[d]);
;                 }
;                 __builtin_amdgcn_sched_barrier(0);
;             }
.LBB0_1056:
	v_sub_f32_e32 v80, v80, v1
	v_exp_f32_e32 v80, v80
	v_sub_f32_e32 v81, v81, v1
	v_exp_f32_e32 v81, v81
	v_sub_f32_e32 v2, v2, v1
	v_exp_f32_e32 v2, v2
	v_sub_f32_e32 v3, v3, v1
	v_exp_f32_e32 v3, v3
	v_sub_f32_e32 v4, v4, v1
	v_add_f32_e32 v82, 0, v80
	v_exp_f32_e32 v4, v4
	v_sub_f32_e32 v5, v5, v1
	v_add_f32_e32 v82, v81, v82
	v_exp_f32_e32 v5, v5
	v_sub_f32_e32 v6, v6, v1
	v_add_f32_e32 v82, v2, v82
	v_exp_f32_e32 v6, v6
	v_sub_f32_e32 v7, v7, v1
	v_add_f32_e32 v82, v3, v82
	v_exp_f32_e32 v7, v7
	v_sub_f32_e32 v8, v8, v1
	v_add_f32_e32 v82, v4, v82
	v_exp_f32_e32 v8, v8
	v_sub_f32_e32 v9, v9, v1
	v_add_f32_e32 v82, v5, v82
	v_exp_f32_e32 v9, v9
	v_sub_f32_e32 v10, v10, v1
	v_add_f32_e32 v82, v6, v82
	v_exp_f32_e32 v10, v10
	v_sub_f32_e32 v11, v11, v1
	v_add_f32_e32 v82, v7, v82
	v_exp_f32_e32 v11, v11
	v_sub_f32_e32 v12, v12, v1
	v_add_f32_e32 v82, v8, v82
	v_exp_f32_e32 v12, v12
	v_sub_f32_e32 v13, v13, v1
	v_add_f32_e32 v82, v9, v82
	v_exp_f32_e32 v13, v13
	v_sub_f32_e32 v14, v14, v1
	v_add_f32_e32 v82, v10, v82
	v_exp_f32_e32 v14, v14
	v_sub_f32_e32 v1, v15, v1
	v_add_f32_e32 v82, v11, v82
	v_exp_f32_e32 v15, v1
	v_add_f32_e32 v82, v12, v82
	v_add_f32_e32 v82, v13, v82
	v_add_f32_e32 v82, v14, v82
	v_add_f32_e32 v82, v15, v82
	v_fmac_f32_e32 v82, v213, v0
	v_cvt_pk_bf16_f32 v0, v80, v81
	v_cvt_pk_bf16_f32 v1, v2, v3
	v_cvt_pk_bf16_f32 v2, v4, v5
	v_cvt_pk_bf16_f32 v3, v6, v7
	v_cvt_pk_bf16_f32 v4, v8, v9
	v_cvt_pk_bf16_f32 v5, v10, v11
	v_cvt_pk_bf16_f32 v6, v12, v13
	v_cvt_pk_bf16_f32 v7, v14, v15
	s_cmp_lg_u32 s35, 0
	s_cbranch_scc1 .Lmla_defer_1
	v_add3_u32 v80, s4, v210, v211
	ds_read_b64_tr_b16 v[216:217], v80 offset:25600
	ds_read_b64_tr_b16 v[218:219], v80 offset:27904
	ds_read_b64_tr_b16 v[220:221], v80 offset:25664
	ds_read_b64_tr_b16 v[222:223], v80 offset:27968
	ds_read_b64_tr_b16 v[224:225], v80 offset:25728
	ds_read_b64_tr_b16 v[226:227], v80 offset:28032
	ds_read_b64_tr_b16 v[228:229], v80 offset:25792
	ds_read_b64_tr_b16 v[230:231], v80 offset:28096
	ds_read_b64_tr_b16 v[232:233], v80 offset:30208
	ds_read_b64_tr_b16 v[234:235], v80 offset:32512
	ds_read_b64_tr_b16 v[236:237], v80 offset:30272
	ds_read_b64_tr_b16 v[238:239], v80 offset:32576
	s_waitcnt lgkmcnt(10)
	v_mfma_f32_32x32x16_bf16 v[64:79], v[216:219], v[0:3], v[64:79]
	ds_read_b64_tr_b16 v[240:241], v80 offset:30336
	ds_read_b64_tr_b16 v[242:243], v80 offset:32640
	s_waitcnt lgkmcnt(10)
	v_mfma_f32_32x32x16_bf16 v[48:63], v[220:223], v[0:3], v[48:63]
	ds_read_b64_tr_b16 v[244:245], v80 offset:30400
	ds_read_b64_tr_b16 v[246:247], v80 offset:32704
	s_waitcnt lgkmcnt(10)
	v_mfma_f32_32x32x16_bf16 v[32:47], v[224:227], v[0:3], v[32:47]
	s_waitcnt lgkmcnt(8)
	v_mfma_f32_32x32x16_bf16 v[16:31], v[228:231], v[0:3], v[16:31]
	s_waitcnt lgkmcnt(6)
	v_mfma_f32_32x32x16_bf16 v[64:79], v[232:235], v[4:7], v[64:79]
	s_waitcnt lgkmcnt(4)
	v_mfma_f32_32x32x16_bf16 v[48:63], v[236:239], v[4:7], v[48:63]
	s_waitcnt lgkmcnt(2)
	v_mfma_f32_32x32x16_bf16 v[32:47], v[240:243], v[4:7], v[32:47]
	s_waitcnt lgkmcnt(0)
	v_mfma_f32_32x32x16_bf16 v[16:31], v[244:247], v[4:7], v[16:31]
	s_branch .Lmla_pvdone_1
.Lmla_defer_1:
	s_mov_b32 s101, 1
.Lmla_pvdone_1:
	v_mov_b32_e32 v213, v82
	s_branch .LBB0_1058

; DI s16x4 vtr(const LAS unsigned char* p) { return __builtin_bit_cast(s16x4, __builtin_amdgcn_ds_read_tr16_b64_v4i16((LAS v4i16_t*)p)); }
; #define MFMA32(a, b, c) __builtin_amdgcn_mfma_f32_32x32x16_bf16((a), (b), (c), 0, 0, 0)
; template <bool ATOM>
; DI void mla_unit(LAS unsigned char* lds, const AttnPtrs& P, int b, int hd, int qb) {
;     ...
;             for (int s2 = 0; s2 < 2; ++s2) {
;                 const bf16x8 pf = pack_step(x0, s2);
; #pragma unroll
;                 for (int d = 0; d < NDV; ++d) {
;                     const s16x4 lo = vtr(Vw + (16 * s2) * VSTR + d * 64), hi = vtr(Vw + (16 * s2 + 8) * VSTR + d * 64);
;                     const bf16x8 pa = __builtin_shufflevector(lo, hi, 0, 1, 2, 3, 4, 5, 6, 7);
;                     o[d] = MFMA32(pa, pf, o[d]);
;                 }
;                 __builtin_amdgcn_sched_barrier(0);
;             }
;         }
;         __syncthreads();
;     }
.LBB0_1058:
	s_mov_b32 s100, s23
	s_add_i32 s14, s14, 64
	s_cmp_eq_u32 s37, s14
	s_waitcnt lgkmcnt(0)
	s_barrier
	s_cbranch_scc1 .LBB0_1060
	v_mov_b32_e32 v124, v212
	s_mov_b32 s4, s38
	s_branch .LBB0_1049
.LBB0_1060:
	s_cmp_eq_u32 s101, 0
	s_cbranch_scc1 .Lmla_noflush_1
	s_sub_i32 s4, s100, 0xac00
	s_cmp_lt_i32 s4, 0
	s_cselect_b32 s4, 0x15800, s4
	v_add3_u32 v80, s4, v210, v211
	ds_read_b64_tr_b16 v[216:217], v80 offset:25600
	ds_read_b64_tr_b16 v[218:219], v80 offset:27904
	ds_read_b64_tr_b16 v[220:221], v80 offset:25664
	ds_read_b64_tr_b16 v[222:223], v80 offset:27968
	ds_read_b64_tr_b16 v[224:225], v80 offset:25728
	ds_read_b64_tr_b16 v[226:227], v80 offset:28032
	ds_read_b64_tr_b16 v[228:229], v80 offset:25792
	ds_read_b64_tr_b16 v[230:231], v80 offset:28096
	ds_read_b64_tr_b16 v[232:233], v80 offset:30208
	ds_read_b64_tr_b16 v[234:235], v80 offset:32512
	ds_read_b64_tr_b16 v[236:237], v80 offset:30272
	ds_read_b64_tr_b16 v[238:239], v80 offset:32576
	s_waitcnt lgkmcnt(10)
	v_mfma_f32_32x32x16_bf16 v[64:79], v[216:219], v[0:3], v[64:79]
	ds_read_b64_tr_b16 v[240:241], v80 offset:30336
	ds_read_b64_tr_b16 v[242:243], v80 offset:32640
	s_waitcnt lgkmcnt(10)
	v_mfma_f32_32x32x16_bf16 v[48:63], v[220:223], v[0:3], v[48:63]
	ds_read_b64_tr_b16 v[244:245], v80 offset:30400
	ds_read_b64_tr_b16 v[246:247], v80 offset:32704
	s_waitcnt lgkmcnt(10)
	v_mfma_f32_32x32x16_bf16 v[32:47], v[224:227], v[0:3], v[32:47]
	s_waitcnt lgkmcnt(8)
	v_mfma_f32_32x32x16_bf16 v[16:31], v[228:231], v[0:3], v[16:31]
	s_waitcnt lgkmcnt(6)
	v_mfma_f32_32x32x16_bf16 v[64:79], v[232:235], v[4:7], v[64:79]
	s_waitcnt lgkmcnt(4)
	v_mfma_f32_32x32x16_bf16 v[48:63], v[236:239], v[4:7], v[48:63]
	s_waitcnt lgkmcnt(2)
	v_mfma_f32_32x32x16_bf16 v[32:47], v[240:243], v[4:7], v[32:47]
	s_waitcnt lgkmcnt(0)
	v_mfma_f32_32x32x16_bf16 v[16:31], v[244:247], v[4:7], v[16:31]
	s_nop 7
	s_nop 3
	s_mov_b32 s101, 0

; DI int opaque_tid() { int t = threadIdx.x; asm volatile("" : "+v"(t)); return t; }
;     DI const bf16_t* Q() const { return (const bf16_t*)(ws + WS_Q); }
;     DI const bf16_t* KV() const { return (const bf16_t*)(ws + WS_KV); }
;     DI const bf16_t* KPE() const { return (const bf16_t*)(ws + WS_KPE); }
; #define MLA_LOAD() do { sreg[0] = *(const u32x4*)(kp0); sreg[1] = *(const u32x4*)(kp0 + 64); sreg[2] = *(const u32x4*)(kp0 + 128); sreg[3] = *(const u32x4*)(kp0 + 192); \
;         sreg[4] = *(const u32x4*)(kp1); kp0 += (size_t)64 * 2048; kp1 += (size_t)64 * 64; } while (0)
; #define MLA_WRITE(buf) do { LAS unsigned char* kd_ = lds + (buf) * BUFB + lkey * KSTR + lq * 16; LAS unsigned char* vd_ = lds + (buf) * BUFB + 64 * KSTR + lkey * VSTR + lq * 16; \
;         *(LAS u32x4*)(kd_) = sreg[0]; *(LAS u32x4*)(kd_ + 128) = sreg[1]; *(LAS u32x4*)(kd_ + 256) = sreg[4]; *(LAS u32x4*)(vd_) = sreg[2]; *(LAS u32x4*)(vd_ + 128) = sreg[3]; } while (0)
; template <bool ATOM>
; DI void mla_unit(LAS unsigned char* lds, const AttnPtrs& P, int b, int hd, int qb) {
;     ...
;     const int tid = opaque_tid(), lane = tid & 63, wid = __builtin_amdgcn_readfirstlane(tid >> 6), r = lane & 31, h = lane >> 5, rg = wid & 3, kh = wid >> 2;
;     const int fq_ = qb * 128 + rg * 32 + r;
;     const size_t tokq = (size_t)b * 2048 + fq_;
;     bf16x8 qf[NKK];
;     { const bf16_t* qp = P.Q() + tokq * 1536 + hd * 192;
; #pragma unroll
;       for (int kk = 0; kk < NKK; ++kk) qf[kk] = *(const bf16x8*)(qp + kk * 16 + 8 * h); }
;     f32x16 o[NDV];
; #pragma unroll
;     for (int d = 0; d < NDV; ++d)
; #pragma unroll
;         for (int i = 0; i < 16; ++i) o[d][i] = 0.f;
;     float mrun = -INFINITY, lrun = 0.f;
;     const int lkey = tid >> 3, lq = tid & 7;
;     const bf16_t* kp0 = P.KV() + ((size_t)b * 2048 + lkey) * 2048 + hd * 256 + lq * 8;
;     const bf16_t* kp1 = P.KPE() + ((size_t)b * 2048 + lkey) * 64 + lq * 8;
;     u32x4 sreg[5];
;     ...
;     const int nsteps = 2 * (qb + 1);
;     __syncthreads();
;     MLA_LOAD(); MLA_WRITE(0);
;     MLA_LOAD();
;     __syncthreads();
;     const int kwo = (kh * 32 + r) * KSTR + h * 16;
;     const int vwo = 64 * KSTR + (kh * 32 + 4 * h + ((lane & 15) >> 2)) * VSTR + (16 * ((lane >> 4) & 1) + 4 * (lane & 3)) * 2;
;     for (int t = 0; t < nsteps; ++t) {
.LBB0_1074:
	v_mov_b32_e32 v30, v188
	s_xor_b32 s4, s16, 15
	s_lshl_b32 s19, s4, 7
	v_readfirstlane_b32 s16, v30
	s_bfe_u32 s18, s16, 0x20006
	s_lshl_b32 s14, s18, 5
	v_and_b32_e32 v31, 31, v30
	s_or_b32 s22, s14, s19
	v_or_b32_e32 v214, s22, v31
	v_or_b32_e32 v130, s50, v214
	s_waitcnt lgkmcnt(0)
	v_mov_b64_e32 v[0:1], s[10:11]
	v_mad_u64_u32 v[0:1], s[14:15], v130, s90, v[0:1]
	v_bfe_u32 v32, v30, 5, 1
	v_mad_i32_i24 v1, s51, v207, v1
	s_lshl_b32 s38, s17, 1
	v_lshl_add_u64 v[0:1], v[0:1], 0, s[38:39]
	v_lshlrev_b32_e32 v128, 4, v32
	v_lshl_add_u64 v[0:1], v[0:1], 0, v[128:129]
	global_load_dwordx4 v[180:183], v[0:1], off
	global_load_dwordx4 v[176:179], v[0:1], off offset:32
	global_load_dwordx4 v[172:175], v[0:1], off offset:64
	global_load_dwordx4 v[168:171], v[0:1], off offset:96
	global_load_dwordx4 v[164:167], v[0:1], off offset:128
	global_load_dwordx4 v[160:163], v[0:1], off offset:160
	global_load_dwordx4 v[156:159], v[0:1], off offset:192
	global_load_dwordx4 v[152:155], v[0:1], off offset:224
	global_load_dwordx4 v[148:151], v[0:1], off offset:256
	global_load_dwordx4 v[144:147], v[0:1], off offset:288
	global_load_dwordx4 v[140:143], v[0:1], off offset:320
	global_load_dwordx4 v[136:139], v[0:1], off offset:352
	v_ashrrev_i32_e32 v20, 3, v30
	v_ashrrev_i32_e32 v21, 31, v20
	v_lshl_add_u64 v[0:1], s[50:51], 0, v[20:21]
	v_lshlrev_b64 v[2:3], 12, v[0:1]
	v_lshl_add_u64 v[2:3], s[12:13], 0, v[2:3]
	s_lshl_b32 s38, s48, 1
	v_lshlrev_b32_e32 v4, 4, v30
	v_lshlrev_b64 v[0:1], 7, v[0:1]
	v_lshl_add_u64 v[2:3], v[2:3], 0, s[38:39]
	v_and_b32_e32 v116, 0x70, v4
	v_mov_b32_e32 v117, v129
	v_lshl_add_u64 v[0:1], s[42:43], 0, v[0:1]
	v_lshl_add_u64 v[22:23], v[2:3], 0, v[116:117]
	v_lshl_add_u64 v[24:25], v[0:1], 0, v[116:117]
	s_barrier
	global_load_dwordx4 v[0:3], v[24:25], off
	global_load_dwordx4 v[4:7], v[22:23], off
	global_load_dwordx4 v[8:11], v[22:23], off offset:128
	global_load_dwordx4 v[12:15], v[22:23], off offset:256
	global_load_dwordx4 v[16:19], v[22:23], off offset:384
	v_add_co_u32_e32 v26, vcc, s89, v22
	s_movk_i32 s14, 0x2000
	s_nop 0
	v_addc_co_u32_e32 v27, vcc, 0, v23, vcc
	global_load_dwordx4 v[96:99], v[26:27], off
	global_load_dwordx4 v[100:103], v[26:27], off offset:128
	global_load_dwordx4 v[104:107], v[26:27], off offset:256
	v_add_co_u32_e32 v28, vcc, s14, v24
	s_lshl_b32 s15, s4, 1
	s_nop 0
	v_addc_co_u32_e32 v29, vcc, 0, v25, vcc
	global_load_dwordx4 v[108:111], v[26:27], off offset:384
	global_load_dwordx4 v[112:115], v[28:29], off
	s_movk_i32 s4, 0x190
	v_mul_lo_u32 v117, v20, s4
	v_bfe_u32 v27, v30, 2, 2
	s_movk_i32 s36, 0x120
	v_add3_u32 v26, 0, v117, v116
	s_movk_i32 s34, 0xff90
	s_ashr_i32 s17, s16, 8
	v_mul_lo_u32 v122, v20, s36
	v_mad_u64_u32 v[20:21], s[34:35], v20, s34, v[26:27]
	v_lshlrev_b32_e32 v209, 2, v32
	s_lshl_b32 s23, s17, 5
	s_mov_b64 s[34:35], 0x4000
	v_and_b32_e32 v208, 63, v30
	v_or_b32_e32 v21, s23, v31
	v_or3_b32 v27, v209, v27, s23
	v_lshl_add_u64 v[118:119], v[24:25], 0, s[34:35]
	s_mov_b64 s[34:35], 0x80000
	v_mov_b32_e32 v31, v129
	v_mul_lo_u32 v215, v21, s4
	v_mul_lo_u32 v210, v27, s36
	v_lshl_add_u64 v[120:121], v[22:23], 0, s[34:35]
	v_mov_b32_e32 v21, v129
	v_mov_b32_e32 v22, v129
	v_mov_b32_e32 v23, v129
	v_mov_b32_e32 v24, v129
	v_mov_b32_e32 v25, v129
	v_mov_b32_e32 v27, v129
	v_mov_b32_e32 v28, v129
	v_mov_b32_e32 v29, v129
	v_mov_b32_e32 v131, s51
	s_mov_b32 s14, 0
	s_or_b32 s34, s22, 31
	s_or_b32 s35, s19, 64
	v_or_b32_e32 v123, s23, v209
	v_mov_b32_e32 v213, 0
	v_mov_b32_e32 v124, 0xff800000
	s_mov_b32 s4, 0
	s_waitcnt vmcnt(9)
	ds_write_b128 v26, v[0:3] offset:256
	s_waitcnt vmcnt(8)
	ds_write_b128 v26, v[4:7]
	s_waitcnt vmcnt(7)
	ds_write_b128 v26, v[8:11] offset:128
	s_waitcnt vmcnt(6)
	ds_write_b128 v20, v[12:15] offset:25600
	s_waitcnt vmcnt(5)
	ds_write_b128 v20, v[16:19] offset:25728
	v_and_b32_e32 v0, 16, v30
	v_lshlrev_b32_e32 v1, 2, v30
	v_mov_b32_e32 v30, v129
	v_and_or_b32 v0, v1, 12, v0
	v_mov_b32_e32 v16, v129
	v_mov_b32_e32 v17, v129
	v_mov_b32_e32 v18, v129
	v_mov_b32_e32 v19, v129
	v_mov_b32_e32 v20, v129
	v_mov_b32_e32 v26, v129
	v_mov_b64_e32 v[46:47], v[30:31]
	v_mov_b64_e32 v[62:63], v[30:31]
	v_mov_b64_e32 v[78:79], v[30:31]
	v_lshlrev_b32_e32 v211, 1, v0
	v_mov_b64_e32 v[44:45], v[28:29]
	v_mov_b64_e32 v[42:43], v[26:27]
	v_mov_b64_e32 v[40:41], v[24:25]
	v_mov_b64_e32 v[38:39], v[22:23]
	v_mov_b64_e32 v[36:37], v[20:21]
	v_mov_b64_e32 v[34:35], v[18:19]
	v_mov_b64_e32 v[32:33], v[16:17]
	v_mov_b64_e32 v[60:61], v[28:29]
	v_mov_b64_e32 v[58:59], v[26:27]
	v_mov_b64_e32 v[56:57], v[24:25]
	v_mov_b64_e32 v[54:55], v[22:23]
	v_mov_b64_e32 v[52:53], v[20:21]
	v_mov_b64_e32 v[50:51], v[18:19]
	v_mov_b64_e32 v[48:49], v[16:17]
	v_mov_b64_e32 v[76:77], v[28:29]
	v_mov_b64_e32 v[74:75], v[26:27]
	v_mov_b64_e32 v[72:73], v[24:25]
	v_mov_b64_e32 v[70:71], v[22:23]
	v_mov_b64_e32 v[68:69], v[20:21]
	v_mov_b64_e32 v[66:67], v[18:19]
	v_mov_b64_e32 v[64:65], v[16:17]
	s_waitcnt lgkmcnt(0)
	s_barrier
	s_mov_b32 s100, 0
	s_mov_b32 s101, 0
.LBB0_1075:
	s_add_i32 s36, s4, 1
	s_add_i32 s19, s100, 0xac00
	s_cmp_eq_u32 s19, 0x20400
	s_cselect_b32 s19, 0, s19
	v_add3_u32 v190, s19, v117, v116
	v_add3_u32 v192, s19, v122, v116
	s_cmp_ge_u32 s4, s15
	s_waitcnt vmcnt(4)
	ds_write_b128 v190, v[96:99]
	s_waitcnt vmcnt(3)
	ds_write_b128 v190, v[100:103] offset:128
	s_waitcnt vmcnt(0)
	ds_write_b128 v190, v[112:115] offset:256
	ds_write_b128 v192, v[104:107] offset:25600
	ds_write_b128 v192, v[108:111] offset:25728
	s_cbranch_scc1 .LBB0_1077
	global_load_dwordx4 v[96:99], v[120:121], off
	global_load_dwordx4 v[100:103], v[120:121], off offset:128
	global_load_dwordx4 v[104:107], v[120:121], off offset:256
	global_load_dwordx4 v[108:111], v[120:121], off offset:384
	global_load_dwordx4 v[112:115], v[118:119], off
	v_lshl_add_u64 v[120:121], v[120:121], 0, s[20:21]
	v_lshl_add_u64 v[118:119], v[118:119], 0, s[24:25]
; #define LAS __attribute__((address_space(3)))
; DI int crow(int i, int h) { return (i & 3) + 8 * (i >> 2) + 4 * h; }
; #define MFMA32(a, b, c) __builtin_amdgcn_mfma_f32_32x32x16_bf16((a), (b), (c), 0, 0, 0)
; #define MLA_LOAD() do { sreg[0] = *(const u32x4*)(kp0); sreg[1] = *(const u32x4*)(kp0 + 64); sreg[2] = *(const u32x4*)(kp0 + 128); sreg[3] = *(const u32x4*)(kp0 + 192); \
;         sreg[4] = *(const u32x4*)(kp1); kp0 += (size_t)64 * 2048; kp1 += (size_t)64 * 64; } while (0)
; #define MLA_WRITE(buf) do { LAS unsigned char* kd_ = lds + (buf) * BUFB + lkey * KSTR + lq * 16; LAS unsigned char* vd_ = lds + (buf) * BUFB + 64 * KSTR + lkey * VSTR + lq * 16; \
;         *(LAS u32x4*)(kd_) = sreg[0]; *(LAS u32x4*)(kd_ + 128) = sreg[1]; *(LAS u32x4*)(kd_ + 256) = sreg[4]; *(LAS u32x4*)(vd_) = sreg[2]; *(LAS u32x4*)(vd_ + 128) = sreg[3]; } while (0)
; template <bool ATOM>
; DI void mla_unit(LAS unsigned char* lds, const AttnPtrs& P, int b, int hd, int qb) {
;     ...
;         if (t + 1 < nsteps) MLA_WRITE((t + 1) & 1);
;         if (t + 2 < nsteps) MLA_LOAD();
;         const int keyb = t * 64 + kh * 32;
;         if (keyb <= qb * 128 + rg * 32 + 31) {
;             const LAS unsigned char* Kw = lds + (t & 1) * BUFB + kwo;
;             const LAS unsigned char* Vw = lds + (t & 1) * BUFB + vwo;
;             f32x16 xa, xb;
; #pragma unroll
;             for (int i = 0; i < 16; ++i) { xa[i] = 0.f; xb[i] = 0.f; }
; #pragma unroll
;             for (int kk = 0; kk < NKK; kk += 2) {
;                 const bf16x8 a0 = *(const LAS bf16x8*)(Kw + kk * 32), a1 = *(const LAS bf16x8*)(Kw + kk * 32 + 32);
;                 xa = MFMA32(a0, qf[kk], xa); xb = MFMA32(a1, qf[kk + 1], xb);
;                 if ((kk & 3) == 2) __builtin_amdgcn_sched_barrier(0);
;             }
;             f32x16 x0;
; #pragma unroll
;             for (int i = 0; i < 16; ++i) x0[i] = xa[i] + xb[i];
;             if (keyb + 31 > qb * 128 + rg * 32) {
; #pragma unroll
;                 for (int i = 0; i < 16; ++i) if (keyb + crow(i, h) > fq_) x0[i] = -INFINITY;
;             }
.LBB0_1077:
	s_cmp_eq_u32 s101, 0
	s_cbranch_scc1 .Lmla_nopend_2
	s_sub_i32 s37, s100, 0xac00
	s_cmp_lt_i32 s37, 0
	s_cselect_b32 s37, 0x15800, s37
	v_add3_u32 v80, s37, v210, v211
	ds_read_b64_tr_b16 v[216:217], v80 offset:25600
	ds_read_b64_tr_b16 v[218:219], v80 offset:27904
	ds_read_b64_tr_b16 v[220:221], v80 offset:25664
	ds_read_b64_tr_b16 v[222:223], v80 offset:27968
	ds_read_b64_tr_b16 v[224:225], v80 offset:25728
	ds_read_b64_tr_b16 v[226:227], v80 offset:28032
	ds_read_b64_tr_b16 v[228:229], v80 offset:25792
	ds_read_b64_tr_b16 v[230:231], v80 offset:28096
	ds_read_b64_tr_b16 v[232:233], v80 offset:30208
	ds_read_b64_tr_b16 v[234:235], v80 offset:32512
	ds_read_b64_tr_b16 v[236:237], v80 offset:30272
	ds_read_b64_tr_b16 v[238:239], v80 offset:32576
	s_waitcnt lgkmcnt(10)
	v_mfma_f32_32x32x16_bf16 v[64:79], v[216:219], v[0:3], v[64:79]
	ds_read_b64_tr_b16 v[240:241], v80 offset:30336
	ds_read_b64_tr_b16 v[242:243], v80 offset:32640
	s_waitcnt lgkmcnt(10)
	v_mfma_f32_32x32x16_bf16 v[48:63], v[220:223], v[0:3], v[48:63]
	ds_read_b64_tr_b16 v[244:245], v80 offset:30400
	ds_read_b64_tr_b16 v[246:247], v80 offset:32704
	s_waitcnt lgkmcnt(10)
	v_mfma_f32_32x32x16_bf16 v[32:47], v[224:227], v[0:3], v[32:47]
	s_waitcnt lgkmcnt(8)
	v_mfma_f32_32x32x16_bf16 v[16:31], v[228:231], v[0:3], v[16:31]
	s_waitcnt lgkmcnt(6)
	v_mfma_f32_32x32x16_bf16 v[64:79], v[232:235], v[4:7], v[64:79]
	s_waitcnt lgkmcnt(4)
	v_mfma_f32_32x32x16_bf16 v[48:63], v[236:239], v[4:7], v[48:63]
	s_waitcnt lgkmcnt(2)
	v_mfma_f32_32x32x16_bf16 v[32:47], v[240:243], v[4:7], v[32:47]
	s_waitcnt lgkmcnt(0)
	v_mfma_f32_32x32x16_bf16 v[16:31], v[244:247], v[4:7], v[16:31]
	s_nop 7
	s_nop 3
	s_mov_b32 s101, 0
.Lmla_nopend_2:
	s_add_i32 s37, s23, s14
	s_cmp_gt_i32 s37, s34
	s_cbranch_scc1 .LBB0_1083
	s_mov_b32 s4, s100
	v_add3_u32 v125, s4, v215, v128
	ds_read_b128 v[0:3], v125
	ds_read_b128 v[80:83], v125 offset:32
	ds_read_b128 v[216:219], v125 offset:64
	s_waitcnt lgkmcnt(2)
	v_mfma_f32_32x32x16_bf16 v[0:15], v[0:3], v[180:183], 0
	s_waitcnt lgkmcnt(0)
	v_mfma_f32_32x32x16_bf16 v[0:15], v[216:219], v[172:175], v[0:15]
	ds_read_b128 v[216:219], v125 offset:96
	v_mfma_f32_32x32x16_bf16 v[0:15], v[80:83], v[176:179], v[0:15]
	s_waitcnt lgkmcnt(0)
	v_mfma_f32_32x32x16_bf16 v[0:15], v[216:219], v[168:171], v[0:15]
	ds_read_b128 v[216:219], v125 offset:128
	s_waitcnt lgkmcnt(0)
	v_mfma_f32_32x32x16_bf16 v[0:15], v[216:219], v[164:167], v[0:15]
	ds_read_b128 v[216:219], v125 offset:160
	s_waitcnt lgkmcnt(0)
	v_mfma_f32_32x32x16_bf16 v[0:15], v[216:219], v[160:163], v[0:15]
	ds_read_b128 v[216:219], v125 offset:192
	s_waitcnt lgkmcnt(0)
	v_mfma_f32_32x32x16_bf16 v[0:15], v[216:219], v[156:159], v[0:15]
	ds_read_b128 v[216:219], v125 offset:224
	s_waitcnt lgkmcnt(0)
	v_mfma_f32_32x32x16_bf16 v[0:15], v[216:219], v[152:155], v[0:15]
	ds_read_b128 v[216:219], v125 offset:256
	s_waitcnt lgkmcnt(0)
	v_mfma_f32_32x32x16_bf16 v[0:15], v[216:219], v[148:151], v[0:15]
	ds_read_b128 v[216:219], v125 offset:288
	s_waitcnt lgkmcnt(0)
	v_mfma_f32_32x32x16_bf16 v[0:15], v[216:219], v[144:147], v[0:15]
	ds_read_b128 v[216:219], v125 offset:320
	s_waitcnt lgkmcnt(0)
	v_mfma_f32_32x32x16_bf16 v[0:15], v[216:219], v[140:143], v[0:15]
	ds_read_b128 v[216:219], v125 offset:352
	s_waitcnt lgkmcnt(0)
	v_mfma_f32_32x32x16_bf16 v[0:15], v[216:219], v[136:139], v[0:15]
	s_add_i32 s37, s37, 31
	s_nop 10
	v_mov_b32_e32 v80, v0
	v_mov_b32_e32 v81, v1
	s_cmp_le_i32 s37, s22
	s_cbranch_scc1 .LBB0_1080
	v_add_u32_e32 v0, s14, v123
	v_cmp_lt_i32_e32 vcc, v0, v214
	v_add_u32_e32 v1, 2, v0
	s_nop 0
	v_cndmask_b32_e32 v81, v205, v81, vcc
	v_cmp_le_i32_e32 vcc, v0, v214
	s_nop 1
	v_cndmask_b32_e32 v80, v205, v80, vcc
	v_cmp_le_i32_e32 vcc, v1, v214
	v_add_u32_e32 v1, 3, v0
	s_nop 0
	v_cndmask_b32_e32 v2, v205, v2, vcc
	v_cmp_le_i32_e32 vcc, v1, v214
	v_add_u32_e32 v1, 8, v0
	s_nop 0
	v_cndmask_b32_e32 v3, v205, v3, vcc
	v_cmp_le_i32_e32 vcc, v1, v214
	v_add_u32_e32 v1, 9, v0
	s_nop 0
	v_cndmask_b32_e32 v4, v205, v4, vcc
	v_cmp_le_i32_e32 vcc, v1, v214
	v_add_u32_e32 v1, 10, v0
	s_nop 0
	v_cndmask_b32_e32 v5, v205, v5, vcc
	v_cmp_le_i32_e32 vcc, v1, v214
	v_add_u32_e32 v1, 11, v0
	s_nop 0
	v_cndmask_b32_e32 v6, v205, v6, vcc
	v_cmp_le_i32_e32 vcc, v1, v214
	v_add_u32_e32 v1, 16, v0
	s_nop 0
	v_cndmask_b32_e32 v7, v205, v7, vcc
	v_cmp_le_i32_e32 vcc, v1, v214
	v_add_u32_e32 v1, 17, v0
	s_nop 0
	v_cndmask_b32_e32 v8, v205, v8, vcc
	v_cmp_le_i32_e32 vcc, v1, v214
	v_add_u32_e32 v1, 18, v0
	s_nop 0
	v_cndmask_b32_e32 v9, v205, v9, vcc
	v_cmp_le_i32_e32 vcc, v1, v214
	v_add_u32_e32 v1, 19, v0
	s_nop 0
	v_cndmask_b32_e32 v10, v205, v10, vcc
	v_cmp_le_i32_e32 vcc, v1, v214
	v_add_u32_e32 v1, 24, v0
	s_nop 0
	v_cndmask_b32_e32 v11, v205, v11, vcc
	v_cmp_le_i32_e32 vcc, v1, v214
	v_add_u32_e32 v1, 25, v0
	s_nop 0
	v_cndmask_b32_e32 v12, v205, v12, vcc
	v_cmp_le_i32_e32 vcc, v1, v214
	v_add_u32_e32 v1, 26, v0
	v_add_u32_e32 v0, 27, v0
	v_cndmask_b32_e32 v13, v205, v13, vcc
	v_cmp_le_i32_e32 vcc, v1, v214
	s_nop 1
	v_cndmask_b32_e32 v14, v205, v14, vcc
	v_cmp_le_i32_e32 vcc, v0, v214
	s_nop 1
	v_cndmask_b32_e32 v15, v205, v15, vcc

; DI float fexp2(float x) { return __builtin_amdgcn_exp2f(x); }
; DI s16x4 vtr(const LAS unsigned char* p) { return __builtin_bit_cast(s16x4, __builtin_amdgcn_ds_read_tr16_b64_v4i16((LAS v4i16_t*)p)); }
; #define MFMA32(a, b, c) __builtin_amdgcn_mfma_f32_32x32x16_bf16((a), (b), (c), 0, 0, 0)
; template <bool ATOM>
; DI void mla_unit(LAS unsigned char* lds, const AttnPtrs& P, int b, int hd, int qb) {
;     ...
;             for (int i = 0; i < 16; ++i) { x0[i] = fexp2(x0[i] - msafe); psum += x0[i]; }
;             lrun = lrun * alpha + psum; mrun = mnew;
;             if (__builtin_amdgcn_ballot_w64(alpha != 1.f) != 0ull) {
; #pragma unroll
;                 for (int d = 0; d < NDV; ++d)
; #pragma unroll
;                     for (int i = 0; i < 16; ++i) o[d][i] *= alpha;
;             }
; #pragma unroll
;             for (int s2 = 0; s2 < 2; ++s2) {
;                 const bf16x8 pf = pack_step(x0, s2);
; #pragma unroll
;                 for (int d = 0; d < NDV; ++d) {
;                     const s16x4 lo = vtr(Vw + (16 * s2) * VSTR + d * 64), hi = vtr(Vw + (16 * s2 + 8) * VSTR + d * 64);
;                     const bf16x8 pa = __builtin_shufflevector(lo, hi, 0, 1, 2, 3, 4, 5, 6, 7);
;                     o[d] = MFMA32(pa, pf, o[d]);
;                 }
;                 __builtin_amdgcn_sched_barrier(0);
;             }
.LBB0_1082:
	v_sub_f32_e32 v80, v80, v1
	v_exp_f32_e32 v80, v80
	v_sub_f32_e32 v81, v81, v1
	v_exp_f32_e32 v81, v81
	v_sub_f32_e32 v2, v2, v1
	v_exp_f32_e32 v2, v2
	v_sub_f32_e32 v3, v3, v1
	v_exp_f32_e32 v3, v3
	v_sub_f32_e32 v4, v4, v1
	v_add_f32_e32 v82, 0, v80
	v_exp_f32_e32 v4, v4
	v_sub_f32_e32 v5, v5, v1
	v_add_f32_e32 v82, v81, v82
	v_exp_f32_e32 v5, v5
	v_sub_f32_e32 v6, v6, v1
	v_add_f32_e32 v82, v2, v82
	v_exp_f32_e32 v6, v6
	v_sub_f32_e32 v7, v7, v1
	v_add_f32_e32 v82, v3, v82
	v_exp_f32_e32 v7, v7
	v_sub_f32_e32 v8, v8, v1
	v_add_f32_e32 v82, v4, v82
	v_exp_f32_e32 v8, v8
	v_sub_f32_e32 v9, v9, v1
	v_add_f32_e32 v82, v5, v82
	v_exp_f32_e32 v9, v9
	v_sub_f32_e32 v10, v10, v1
	v_add_f32_e32 v82, v6, v82
	v_exp_f32_e32 v10, v10
	v_sub_f32_e32 v11, v11, v1
	v_add_f32_e32 v82, v7, v82
	v_exp_f32_e32 v11, v11
	v_sub_f32_e32 v12, v12, v1
	v_add_f32_e32 v82, v8, v82
	v_exp_f32_e32 v12, v12
	v_sub_f32_e32 v13, v13, v1
	v_add_f32_e32 v82, v9, v82
	v_exp_f32_e32 v13, v13
	v_sub_f32_e32 v14, v14, v1
	v_add_f32_e32 v82, v10, v82
	v_exp_f32_e32 v14, v14
	v_sub_f32_e32 v1, v15, v1
	v_add_f32_e32 v82, v11, v82
	v_exp_f32_e32 v15, v1
	v_add_f32_e32 v82, v12, v82
	v_add_f32_e32 v82, v13, v82
	v_add_f32_e32 v82, v14, v82
	v_add_f32_e32 v82, v15, v82
	v_fmac_f32_e32 v82, v213, v0
	v_cvt_pk_bf16_f32 v0, v80, v81
	v_cvt_pk_bf16_f32 v1, v2, v3
	v_cvt_pk_bf16_f32 v2, v4, v5
	v_cvt_pk_bf16_f32 v3, v6, v7
	v_cvt_pk_bf16_f32 v4, v8, v9
	v_cvt_pk_bf16_f32 v5, v10, v11
	v_cvt_pk_bf16_f32 v6, v12, v13
	v_cvt_pk_bf16_f32 v7, v14, v15
	s_cmp_lg_u32 s23, 0
	s_cbranch_scc1 .Lmla_defer_2
	v_add3_u32 v80, s4, v210, v211
	ds_read_b64_tr_b16 v[216:217], v80 offset:25600
	ds_read_b64_tr_b16 v[218:219], v80 offset:27904
	ds_read_b64_tr_b16 v[220:221], v80 offset:25664
	ds_read_b64_tr_b16 v[222:223], v80 offset:27968
	ds_read_b64_tr_b16 v[224:225], v80 offset:25728
	ds_read_b64_tr_b16 v[226:227], v80 offset:28032
	ds_read_b64_tr_b16 v[228:229], v80 offset:25792
	ds_read_b64_tr_b16 v[230:231], v80 offset:28096
	ds_read_b64_tr_b16 v[232:233], v80 offset:30208
	ds_read_b64_tr_b16 v[234:235], v80 offset:32512
	ds_read_b64_tr_b16 v[236:237], v80 offset:30272
	ds_read_b64_tr_b16 v[238:239], v80 offset:32576
	s_waitcnt lgkmcnt(10)
	v_mfma_f32_32x32x16_bf16 v[64:79], v[216:219], v[0:3], v[64:79]
	ds_read_b64_tr_b16 v[240:241], v80 offset:30336
	ds_read_b64_tr_b16 v[242:243], v80 offset:32640
	s_waitcnt lgkmcnt(10)
	v_mfma_f32_32x32x16_bf16 v[48:63], v[220:223], v[0:3], v[48:63]
	ds_read_b64_tr_b16 v[244:245], v80 offset:30400
	ds_read_b64_tr_b16 v[246:247], v80 offset:32704
	s_waitcnt lgkmcnt(10)
	v_mfma_f32_32x32x16_bf16 v[32:47], v[224:227], v[0:3], v[32:47]
	s_waitcnt lgkmcnt(8)
	v_mfma_f32_32x32x16_bf16 v[16:31], v[228:231], v[0:3], v[16:31]
	s_waitcnt lgkmcnt(6)
	v_mfma_f32_32x32x16_bf16 v[64:79], v[232:235], v[4:7], v[64:79]
	s_waitcnt lgkmcnt(4)
	v_mfma_f32_32x32x16_bf16 v[48:63], v[236:239], v[4:7], v[48:63]
	s_waitcnt lgkmcnt(2)
	v_mfma_f32_32x32x16_bf16 v[32:47], v[240:243], v[4:7], v[32:47]
	s_waitcnt lgkmcnt(0)
	v_mfma_f32_32x32x16_bf16 v[16:31], v[244:247], v[4:7], v[16:31]
	s_branch .Lmla_pvdone_2

; #define MLA_LOAD() do { sreg[0] = *(const u32x4*)(kp0); sreg[1] = *(const u32x4*)(kp0 + 64); sreg[2] = *(const u32x4*)(kp0 + 128); sreg[3] = *(const u32x4*)(kp0 + 192); \
;         sreg[4] = *(const u32x4*)(kp1); kp0 += (size_t)64 * 2048; kp1 += (size_t)64 * 64; } while (0)
; #define MLA_WRITE(buf) do { LAS unsigned char* kd_ = lds + (buf) * BUFB + lkey * KSTR + lq * 16; LAS unsigned char* vd_ = lds + (buf) * BUFB + 64 * KSTR + lkey * VSTR + lq * 16; \
;         *(LAS u32x4*)(kd_) = sreg[0]; *(LAS u32x4*)(kd_ + 128) = sreg[1]; *(LAS u32x4*)(kd_ + 256) = sreg[4]; *(LAS u32x4*)(vd_) = sreg[2]; *(LAS u32x4*)(vd_ + 128) = sreg[3]; } while (0)
; template <bool ATOM>
; DI void mla_unit(LAS unsigned char* lds, const AttnPtrs& P, int b, int hd, int qb) {
;     ...
;     for (int t = 0; t < nsteps; ++t) {
;         if (t + 1 < nsteps) MLA_WRITE((t + 1) & 1);
;         if (t + 2 < nsteps) MLA_LOAD();
;         const int keyb = t * 64 + kh * 32;
.LBB0_1084:
	s_mov_b32 s100, s19
	s_add_i32 s14, s14, 64
	s_cmp_eq_u32 s35, s14
	s_waitcnt lgkmcnt(0)
	s_barrier
	s_cbranch_scc1 .LBB0_1086
	v_mov_b32_e32 v124, v212
	s_mov_b32 s4, s36
	s_branch .LBB0_1075
